# P2a weight transposes as a per-XCD sharded atomic work queue over all waves (was 44 items on 128 fixed workgroups); plus batched P3/P4/P6 epilogue loads, pass-C XCD remap, GLA A1 pipelining, early L2
# speedup vs baseline: 1.0236x; 1.0039x over previous
; #define LAS __attribute__((address_space(3)))
; __global__ void __launch_bounds__(512) mk_fwd(Args a) {
;     ...
;             if (G == 256 && blk >= 96 && blk < NA && rsw == 0) {
;                 __syncthreads();
;                 const int wv = tl >> 6; LAS float* scr = (LAS float*)(lds + wv * 12288);
;                 for (int q = wv; q < 44; q += 8) transpose_rest_item(P, (blk - 96) * 44 + q, scr, tl & 63);
;             }
.LBB0_351:
	s_add_i32 s0, s2, 0xffffffa0
	s_cmp_eq_u32 s0, s0
	v_readlane_b32 s4, v246, 5
	s_cselect_b64 s[0:1], -1, 0
	v_readlane_b32 s5, v246, 6
	s_and_b64 s[0:1], s[0:1], s[4:5]
	s_and_b64 vcc, exec, s[0:1]
	s_cbranch_vccz .LBB0_374
	v_ashrrev_i32_e32 v0, 6, v190
	v_cmp_gt_i32_e32 vcc, 44, v0
	s_barrier
	s_and_saveexec_b64 s[0:1], vcc
	s_cbranch_execz .LBB0_373
	s_movk_i32 s4, 0x3000
	v_mul_lo_u32 v1, v0, s4
	v_and_b32_e32 v2, 7, v190
	v_readlane_b32 s4, v246, 7
	v_lshlrev_b32_e32 v32, 4, v2
	v_mov_b32_e32 v33, 0
	v_readlane_b32 s5, v246, 8
	s_movk_i32 s3, 0x1078
	v_add_u32_e32 v1, 0, v1
	v_lshl_add_u64 v[36:37], s[4:5], 0, v[32:33]
	v_readlane_b32 s4, v246, 13
	v_readlane_b32 s5, v246, 14
	v_bfe_u32 v54, v190, 3, 3
	v_add_u32_e32 v3, v1, v32
	v_lshl_add_u64 v[40:41], s[4:5], 0, v[32:33]
	v_readlane_b32 s4, v246, 11
	v_readlane_b32 s5, v246, 12
	v_mul_u32_u24_e32 v4, 0x84, v54
	v_lshl_add_u32 v59, s2, 3, v0
	v_lshl_add_u64 v[44:45], s[4:5], 0, v[32:33]
	v_readlane_b32 s4, v246, 16
	v_mov_b32_e32 v0, v59
	v_mul_u32_u24_e32 v2, 0x420, v2
	v_lshlrev_b32_e32 v5, 2, v54
	v_readlane_b32 s5, v246, 17
	s_nop 0
	v_add_u32_e32 v62, v3, v4
	v_lshl_add_u64 v[34:35], s[48:49], 0, v[32:33]
	v_or_b32_e32 v55, 8, v54
	v_or_b32_e32 v56, 16, v54
	v_or_b32_e32 v57, 24, v54
	v_add3_u32 v58, v1, v2, v5
	v_lshl_add_u64 v[38:39], s[46:47], 0, v[32:33]
	v_lshl_add_u64 v[42:43], s[42:43], 0, v[32:33]
	v_lshl_add_u64 v[46:47], s[40:41], 0, v[32:33]
	v_lshl_add_u64 v[48:49], s[4:5], 0, v[32:33]
	v_lshl_add_u64 v[50:51], s[38:39], 0, v[32:33]
	v_lshl_add_u64 v[52:53], s[76:77], 0, v[32:33]
	v_lshlrev_b32_e32 v60, 5, v0
	v_lshlrev_b32_e32 v61, 1, v0
	v_readlane_b32 s100, v246, 1
	v_readlane_b32 s101, v246, 2
	v_mov_b32_e32 v97, 1
	s_and_b32 s98, s2, 7
	s_mul_i32 s99, s98, 0x1c0
	s_addk_i32 s99, 0x800
	v_mov_b32_e32 v95, s99
	s_lshl_b32 s98, s98, 8
	s_addk_i32 s98, 0x3700
	v_mov_b32_e32 v98, s98
	s_mov_b64 s[4:5], 0
	s_movk_i32 s8, 0x1ff
	s_movk_i32 s9, 0x3ff
	s_movk_i32 s16, 0x5ff
	s_movk_i32 s17, 0xdff
	v_add_u32_e32 v63, 0x420, v62
	v_add_u32_e32 v64, 0x428, v62
	v_add_u32_e32 v65, 0x840, v62
	v_add_u32_e32 v66, 0x848, v62
	v_add_u32_e32 v67, 0xc60, v62
	v_add_u32_e32 v68, 0xc68, v62
	v_add_u32_e32 v69, 0x1080, v62
	v_add_u32_e32 v70, 0x1088, v62
	v_add_u32_e32 v71, 0x14a0, v62
	v_add_u32_e32 v72, 0x14a8, v62
	v_add_u32_e32 v73, 0x18c0, v62
	v_add_u32_e32 v74, 0x18c8, v62
	v_add_u32_e32 v75, 0x1ce0, v62
	v_add_u32_e32 v76, 0x1ce8, v62
	s_branch .LBB0_355
.LBB0_354:
	s_or_b64 exec, exec, s[6:7]
	s_waitcnt vmcnt(4)
	v_readfirstlane_b32 s98, v96
	s_nop 3
	v_mov_b32_e32 v59, s98
	v_cmp_lt_u32_e32 vcc, 0x1bf, v59
	v_add_u32_e32 v59, v95, v59
	v_lshlrev_b32_e32 v60, 5, v59
	s_or_b64 s[4:5], vcc, s[4:5]
	v_lshlrev_b32_e32 v61, 1, v59
	s_andn2_b64 exec, exec, s[4:5]
	s_cbranch_execz .LBB0_373
; #define LAS __attribute__((address_space(3)))
; #define LDS_WAIT() asm volatile("s_waitcnt lgkmcnt(0)" ::: "memory")
; __device__ __forceinline__ void transpose_item(const float* __restrict__ W, int ldw, int K, bf16_t* WT, int dst_row0, int src_col0, int nvalid, const float* __restrict__ kscale, int k0, LAS float* scr, int lane) {
;     const int c4 = lane & 7, kr = lane >> 3;
;     f32x4 v[8];
; #pragma unroll
;     for (int i = 0; i < 8; ++i) { v[i] = (f32x4){0.f, 0.f, 0.f, 0.f};
;         if (4 * c4 < nvalid) v[i] = __builtin_nontemporal_load((const f32x4*)(W + (size_t)(k0 + kr + 8 * i) * ldw + src_col0 + 4 * c4)); }
;     if (kscale) {
; #pragma unroll
;         for (int i = 0; i < 8; ++i) v[i] = v[i] * kscale[k0 + kr + 8 * i];
;     }
; #pragma unroll
;     for (int i = 0; i < 8; ++i) { LAS float* d = scr + (kr + 8 * i) * 33 + 4 * c4; d[0] = v[i].x; d[1] = v[i].y; d[2] = v[i].z; d[3] = v[i].w; }
;     LDS_WAIT(); asm volatile("" ::: "memory");
;     const int ch = lane & 7;
; #pragma unroll
;     for (int j = 0; j < 4; ++j) { const int n = (lane >> 3) + 8 * j; const LAS float* s = scr + (8 * ch) * 33 + n;
;         u32x4 o; o.x = pk2(s[0 * 33], s[1 * 33]); o.y = pk2(s[2 * 33], s[3 * 33]); o.z = pk2(s[4 * 33], s[5 * 33]); o.w = pk2(s[6 * 33], s[7 * 33]);
;         *(u32x4*)(WT + (size_t)(dst_row0 + n) * K + k0 + 8 * ch) = o; }
;     LDS_WAIT(); asm volatile("" ::: "memory");
; }
; __device__ __forceinline__ void transpose_rest_item(const Ptrs& P, int r, LAS float* scr, int lane) {
;     if (r < P0_I_SQ) { transpose_item(P.w_bg, 1024, 1024, (bf16_t*)(P.ws + WS_WBG), 32 * (r % 32), 32 * (r % 32), 32, nullptr, 64 * (r / 32), scr, lane); return; } r -= P0_I_SQ;
;     if (r < P0_I_SQ) { transpose_item(P.w_bs, 1024, 1024, (bf16_t*)(P.ws + WS_WBS), 32 * (r % 32), 32 * (r % 32), 32, nullptr, 64 * (r / 32), scr, lane); return; } r -= P0_I_SQ;
;     if (r < P0_I_SQ) { transpose_item(P.w_out, 1024, 1024, (bf16_t*)(P.ws + WS_WOUT), 32 * (r % 32), 32 * (r % 32), 32, nullptr, 64 * (r / 32), scr, lane); return; } r -= P0_I_SQ;
;     if (r < P0_I_UP) { transpose_item(P.w_up, 4096, 1024, (bf16_t*)(P.ws + WS_WUP), 32 * (r % 128), 32 * (r % 128), 32, P.norm_mlp, 64 * (r / 128), scr, lane); return; } r -= P0_I_UP;
;     transpose_item(P.w_down, 1024, 4096, (bf16_t*)(P.ws + WS_WDN), 32 * (r % 32), 32 * (r % 32), 32, nullptr, 64 * (r / 32), scr, lane);
.LBB0_355:
	v_add_u32_e32 v0, s3, v59
	s_mov_b64 s[98:99], exec
	s_mov_b64 exec, 1
	global_atomic_add v96, v98, v97, s[100:101] sc0
	s_mov_b64 exec, s[98:99]
	v_add_u32_e32 v1, 0xffffef88, v0
	v_cmp_lt_i32_e32 vcc, s8, v1
	s_and_saveexec_b64 s[6:7], vcc
	s_xor_b64 s[6:7], exec, s[6:7]
	s_cbranch_execz .LBB0_371
	v_cmp_lt_u32_e32 vcc, s9, v1
	s_and_saveexec_b64 s[10:11], vcc
	s_xor_b64 s[10:11], exec, s[10:11]
	s_cbranch_execz .LBB0_368
	v_cmp_lt_u32_e32 vcc, s16, v1
	s_and_saveexec_b64 s[12:13], vcc
	s_xor_b64 s[12:13], exec, s[12:13]
	s_cbranch_execz .LBB0_365
	v_cmp_lt_u32_e32 vcc, s17, v1
	s_and_saveexec_b64 s[14:15], vcc
	s_xor_b64 s[14:15], exec, s[14:15]
	s_cbranch_execz .LBB0_360
	v_and_b32_e32 v0, 0x7fffffc0, v61
	v_and_b32_e32 v77, 0x3e0, v60
	v_add_u32_e32 v78, 0xffffe400, v0
	v_or_b32_e32 v28, v78, v54
	v_lshlrev_b32_e32 v32, 2, v77
	v_lshl_add_u64 v[30:31], v[34:35], 0, v[32:33]
	v_or_b32_e32 v32, 8, v28
	v_lshlrev_b64 v[2:3], 12, v[32:33]
	v_or_b32_e32 v32, 16, v28
	v_lshlrev_b64 v[8:9], 12, v[32:33]
	v_or_b32_e32 v32, 24, v28
	v_lshlrev_b64 v[10:11], 12, v[32:33]
	v_or_b32_e32 v32, 32, v28
	v_mov_b32_e32 v29, v33
	v_lshlrev_b64 v[16:17], 12, v[32:33]
	v_or_b32_e32 v32, 40, v28
	v_lshlrev_b64 v[0:1], 12, v[28:29]
	v_lshlrev_b64 v[18:19], 12, v[32:33]
	v_lshl_add_u64 v[0:1], v[30:31], 0, v[0:1]
	v_lshl_add_u64 v[4:5], v[30:31], 0, v[2:3]
	v_lshl_add_u64 v[8:9], v[30:31], 0, v[8:9]
	v_lshl_add_u64 v[12:13], v[30:31], 0, v[10:11]
	v_lshl_add_u64 v[16:17], v[30:31], 0, v[16:17]
	v_lshl_add_u64 v[20:21], v[30:31], 0, v[18:19]
	global_load_dwordx4 v[0:3], v[0:1], off nt
	s_nop 0
	global_load_dwordx4 v[4:7], v[4:5], off nt
	s_nop 0
	global_load_dwordx4 v[8:11], v[8:9], off nt
	s_nop 0
	global_load_dwordx4 v[12:15], v[12:13], off nt
	s_nop 0
	global_load_dwordx4 v[16:19], v[16:17], off nt
	s_nop 0
	global_load_dwordx4 v[20:23], v[20:21], off nt
	v_or_b32_e32 v32, 48, v28
	v_lshlrev_b64 v[24:25], 12, v[32:33]
	v_lshl_add_u64 v[24:25], v[30:31], 0, v[24:25]
	v_or_b32_e32 v32, 56, v28
	global_load_dwordx4 v[24:27], v[24:25], off nt
	v_lshlrev_b64 v[28:29], 12, v[32:33]
	v_lshl_add_u64 v[28:29], v[30:31], 0, v[28:29]
	global_load_dwordx4 v[28:31], v[28:29], off nt
	v_mov_b32_e32 v79, v33
	s_waitcnt vmcnt(7)
	ds_write2_b32 v62, v0, v1 offset1:1
	ds_write2_b32 v62, v2, v3 offset0:2 offset1:3
	s_waitcnt vmcnt(6)
	ds_write2_b32 v63, v4, v5 offset1:1
	ds_write2_b32 v64, v6, v7 offset1:1
	s_waitcnt vmcnt(5)
	ds_write2_b32 v65, v8, v9 offset1:1
	ds_write2_b32 v66, v10, v11 offset1:1
	s_waitcnt vmcnt(4)
	ds_write2_b32 v67, v12, v13 offset1:1
	ds_write2_b32 v68, v14, v15 offset1:1
	s_waitcnt vmcnt(3)
	ds_write2_b32 v69, v16, v17 offset1:1
	ds_write2_b32 v70, v18, v19 offset1:1
	s_waitcnt vmcnt(2)
	ds_write2_b32 v71, v20, v21 offset1:1
	ds_write2_b32 v72, v22, v23 offset1:1
	s_waitcnt vmcnt(1)
	ds_write2_b32 v73, v24, v25 offset1:1
	ds_write2_b32 v74, v26, v27 offset1:1
	s_waitcnt vmcnt(0)
	ds_write2_b32 v75, v28, v29 offset1:1
	ds_write2_b32 v76, v30, v31 offset1:1
	s_waitcnt lgkmcnt(0)
	ds_read2_b32 v[0:1], v58 offset1:33
	s_waitcnt lgkmcnt(0)
	v_cvt_pk_bf16_f32 v0, v0, v1
	ds_read2_b32 v[2:3], v58 offset0:66 offset1:99
	v_or_b32_e32 v8, v77, v54
	s_waitcnt lgkmcnt(0)
	v_cvt_pk_bf16_f32 v1, v2, v3
	ds_read2_b32 v[2:3], v58 offset0:132 offset1:165
	v_lshl_add_u64 v[6:7], v[78:79], 1, v[36:37]
	v_lshlrev_b32_e32 v32, 13, v8
	s_waitcnt lgkmcnt(0)
	v_cvt_pk_bf16_f32 v2, v2, v3
	ds_read2_b32 v[4:5], v58 offset0:198 offset1:231
	s_waitcnt lgkmcnt(0)
	v_cvt_pk_bf16_f32 v3, v4, v5
	v_lshl_add_u64 v[8:9], v[6:7], 0, v[32:33]
	ds_read2_b32 v[4:5], v58 offset0:8 offset1:41
	global_store_dwordx4 v[8:9], v[0:3], off
	v_or_b32_e32 v8, v77, v55
	v_lshlrev_b32_e32 v32, 13, v8
	s_waitcnt lgkmcnt(0)
	v_cvt_pk_bf16_f32 v0, v4, v5
	ds_read2_b32 v[2:3], v58 offset0:74 offset1:107
	s_waitcnt lgkmcnt(0)
	v_cvt_pk_bf16_f32 v1, v2, v3
	ds_read2_b32 v[2:3], v58 offset0:140 offset1:173
	s_waitcnt lgkmcnt(0)
	v_cvt_pk_bf16_f32 v2, v2, v3
	ds_read2_b32 v[4:5], v58 offset0:206 offset1:239
	s_waitcnt lgkmcnt(0)
	v_cvt_pk_bf16_f32 v3, v4, v5
	v_lshl_add_u64 v[8:9], v[6:7], 0, v[32:33]
	ds_read2_b32 v[4:5], v58 offset0:16 offset1:49
	global_store_dwordx4 v[8:9], v[0:3], off
	v_or_b32_e32 v8, v77, v56
	v_lshlrev_b32_e32 v32, 13, v8
	s_waitcnt lgkmcnt(0)
	v_cvt_pk_bf16_f32 v0, v4, v5
	ds_read2_b32 v[2:3], v58 offset0:82 offset1:115
	s_waitcnt lgkmcnt(0)
	v_cvt_pk_bf16_f32 v1, v2, v3
	ds_read2_b32 v[2:3], v58 offset0:148 offset1:181
	s_waitcnt lgkmcnt(0)
	v_cvt_pk_bf16_f32 v2, v2, v3
	ds_read2_b32 v[4:5], v58 offset0:214 offset1:247
	s_waitcnt lgkmcnt(0)
	v_cvt_pk_bf16_f32 v3, v4, v5
	v_lshl_add_u64 v[8:9], v[6:7], 0, v[32:33]
	ds_read2_b32 v[4:5], v58 offset0:24 offset1:57
	global_store_dwordx4 v[8:9], v[0:3], off
	s_waitcnt lgkmcnt(0)
	s_nop 0
	v_cvt_pk_bf16_f32 v0, v4, v5
	ds_read2_b32 v[2:3], v58 offset0:90 offset1:123
	s_waitcnt lgkmcnt(0)
	v_cvt_pk_bf16_f32 v1, v2, v3
	ds_read2_b32 v[2:3], v58 offset0:156 offset1:189
	s_waitcnt lgkmcnt(0)
	v_cvt_pk_bf16_f32 v2, v2, v3
	v_or_b32_e32 v3, v77, v57
	ds_read2_b32 v[4:5], v58 offset0:222 offset1:255
	v_lshlrev_b32_e32 v32, 13, v3
	s_waitcnt lgkmcnt(0)
	v_cvt_pk_bf16_f32 v3, v4, v5
	v_lshl_add_u64 v[4:5], v[6:7], 0, v[32:33]
	global_store_dwordx4 v[4:5], v[0:3], off
	s_waitcnt lgkmcnt(0)
